# norm phase column mapping changed to chunk j at 256j+4*lane: every row load/store instruction covers 1 KiB of contiguous memory (full lines), H stored as 8-byte pieces; on top of v20
# speedup vs baseline: 1.0264x; 1.0096x over previous
.LBB0_501:
	v_readlane_b32 s42, v241, 32
	v_readlane_b32 s44, v241, 34
	v_readlane_b32 s50, v241, 36
	s_andn2_b64 vcc, exec, s[0:1]
	v_readlane_b32 s43, v241, 33
	v_readlane_b32 s45, v241, 35
	s_mov_b32 s46, 0x5c00000
	v_readlane_b32 s47, v241, 42
	v_readlane_b32 s51, v241, 37
	s_mov_b64 s[66:67], 0x1000000
	s_mov_b64 s[80:81], 0x1400000
	s_cbranch_vccnz .LBB0_528
	v_mov_b32_e32 v2, v0
	s_nop 0
	v_readfirstlane_b32 s0, v2
	s_ashr_i32 s4, s0, 6
	s_add_i32 s0, s4, s63
	s_cmp_ge_i32 s0, s57
	s_cbranch_scc1 .LBB0_528
	v_lshlrev_b32_e32 v3, 3, v2
	v_readlane_b32 s0, v241, 56
	v_and_b32_e32 v128, 0x1f8, v3
	v_lshrrev_b32_e32 v128, 1, v128
	v_and_b32_e32 v3, 64, v223
	v_readlane_b32 s1, v241, 57
	v_add_u32_e32 v3, 64, v3
	s_waitcnt lgkmcnt(0)
	v_xor_b32_e32 v5, 1, v223
	s_lshl_b64 s[0:1], s[0:1], 2
	v_readlane_b32 s3, v241, 43
	v_cmp_lt_i32_e32 vcc, v5, v3
	s_add_u32 s16, s3, s0
	v_readlane_b32 s0, v241, 44
	v_cndmask_b32_e32 v5, v223, v5, vcc
	s_addc_u32 s17, s0, s1
	v_lshlrev_b32_e32 v67, 2, v5
	v_xor_b32_e32 v5, 2, v223
	s_cmp_lg_u32 s6, 7
	v_cmp_lt_i32_e32 vcc, v5, v3
	s_cselect_b64 s[0:1], -1, 0
	s_cmp_lg_u32 s47, 0
	v_cndmask_b32_e32 v5, v223, v5, vcc
	s_cselect_b64 s[6:7], -1, 0
	v_lshlrev_b32_e32 v129, 2, v5
	v_xor_b32_e32 v5, 4, v223
	v_lshlrev_b32_e32 v184, 2, v128
	s_lshl_b32 s5, s4, 10
	v_readlane_b32 s3, v242, 62
	v_cmp_lt_i32_e32 vcc, v5, v3
	v_lshl_add_u64 v[6:7], s[74:75], 0, v[184:185]
	s_mov_b64 s[8:9], 0xe400000
	s_add_i32 s78, s3, s5
	s_ashr_i32 s5, s4, 31
	v_cndmask_b32_e32 v5, v223, v5, vcc
	v_lshl_add_u64 v[130:131], v[6:7], 0, s[8:9]
	s_add_u32 s8, s63, s4
	v_readlane_b32 s3, v241, 17
	v_lshlrev_b32_e32 v142, 2, v5
	v_xor_b32_e32 v5, 8, v223
	s_addc_u32 s9, s3, s5
	v_cmp_lt_i32_e32 vcc, v5, v3
	s_lshl_b64 s[10:11], s[8:9], 11
	s_add_u32 s10, s74, s10
	v_cndmask_b32_e32 v5, v223, v5, vcc
	v_readlane_b32 s3, v241, 18
	v_lshlrev_b32_e32 v143, 2, v5
	v_xor_b32_e32 v5, 16, v223
	s_addc_u32 s11, s75, s11
	s_add_i32 s4, s3, s4
	v_cmp_lt_i32_e32 vcc, v5, v3
	s_ashr_i32 s5, s4, 31
	s_lshl_b64 s[20:21], s[4:5], 11
	v_cndmask_b32_e32 v5, v223, v5, vcc
	v_lshlrev_b32_e32 v144, 2, v5
	v_xor_b32_e32 v5, 32, v223
	s_add_u32 s20, s74, s20
	v_cmp_lt_i32_e32 vcc, v5, v3
	s_addc_u32 s21, s75, s21
	s_lshl_b64 s[4:5], s[4:5], 12
	v_or_b32_e32 v4, 0x200, v128
	v_cndmask_b32_e32 v3, v223, v5, vcc
	v_and_b32_e32 v2, 63, v2
	s_add_u32 s22, s90, s4
	v_readlane_b32 s26, v241, 21
	v_lshlrev_b32_e32 v145, 2, v3
	v_lshl_add_u64 v[132:133], s[14:15], 0, v[184:185]
	v_lshlrev_b32_e32 v184, 3, v2
	s_addc_u32 s23, s91, s5
	s_mov_b64 s[24:25], 0
	v_lshlrev_b32_e32 v146, 2, v4
	v_readlane_b32 s27, v241, 22
	s_mov_b64 s[36:37], 0
	s_mov_b64 s[74:75], 0x1800000
	s_branch .LBB0_506
.LBB0_504:
	v_pk_mul_f32 v[22:23], v[28:29], v[28:29]
	v_pk_mul_f32 v[24:25], v[26:27], v[26:27]
	v_pk_mul_f32 v[18:19], v[32:33], v[32:33]
	v_pk_mul_f32 v[20:21], v[30:31], v[30:31]
	v_pk_mov_b32 v[38:39], v[24:25], v[22:23] op_sel:[1,0]
	v_mov_b32_e32 v25, v23
	v_pk_add_f32 v[22:23], v[38:39], v[24:25]
	v_pk_mov_b32 v[24:25], v[20:21], v[18:19] op_sel:[1,0]
	v_mov_b32_e32 v21, v19
	v_pk_add_f32 v[18:19], v[24:25], v[20:21]
	v_pk_add_f32 v[22:23], v[22:23], v[22:23] op_sel_hi:[0,1]
	v_pk_add_f32 v[18:19], v[18:19], v[18:19] op_sel_hi:[0,1]
	v_mul_f32_e32 v18, v34, v34
	v_pk_fma_f32 v[20:21], v[34:35], v[34:35], v[18:19] op_sel_hi:[1,1,0]
	v_mul_f32_e32 v18, v36, v36
	v_pk_fma_f32 v[24:25], v[36:37], v[36:37], v[18:19] op_sel_hi:[1,1,0]
	v_mul_f32_e32 v20, v100, v100
	v_mul_f32_e32 v24, v101, v101
	v_mul_f32_e32 v22, v102, v102
	v_mul_f32_e32 v18, v103, v103
	v_pk_add_f32 v[20:21], v[20:21], v[24:25]
	v_pk_add_f32 v[18:19], v[22:23], v[18:19]
	s_nop 0
	v_pk_add_f32 v[18:19], v[20:21], v[18:19]
	s_nop 0
	v_add_f32_e32 v18, v18, v19
	s_nop 1
	v_add_f32_dpp v18, v18, v18 quad_perm:[1,0,3,2] row_mask:0xf bank_mask:0xf
	s_nop 1
	v_add_f32_dpp v18, v18, v18 quad_perm:[2,3,0,1] row_mask:0xf bank_mask:0xf
	s_nop 1
	v_add_f32_dpp v18, v18, v18 row_half_mirror row_mask:0xf bank_mask:0xf
	s_nop 1
	v_add_f32_dpp v18, v18, v18 row_mirror row_mask:0xf bank_mask:0xf
	s_nop 1
	v_mov_b32_e32 v19, v18
	s_nop 1
	v_permlane16_swap_b32_e32 v18, v19
	s_nop 1
	v_add_f32_e32 v18, v18, v19
	s_nop 1
	v_mov_b32_e32 v19, v18
	s_nop 1
	v_permlane32_swap_b32_e32 v18, v19
	s_nop 1
	v_add_f32_e32 v18, v18, v19
	v_fmamk_f32 v18, v18, 0x3a800000, v1
	v_mul_f32_e32 v19, 0x4f800000, v18
	v_cmp_gt_f32_e32 vcc, s56, v18
	s_nop 1
	v_cndmask_b32_e32 v18, v18, v19, vcc
	v_sqrt_f32_e32 v19, v18
	s_nop 0
	v_add_u32_e32 v20, -1, v19
	v_add_u32_e32 v21, 1, v19
	v_fma_f32 v22, -v20, v19, v18
	v_fma_f32 v23, -v21, v19, v18
	v_cmp_ge_f32_e64 s[38:39], 0, v22
	s_nop 1
	v_cndmask_b32_e64 v19, v19, v20, s[38:39]
	v_cmp_lt_f32_e64 s[38:39], 0, v23
	s_nop 1
	v_cndmask_b32_e64 v19, v19, v21, s[38:39]
	v_mul_f32_e32 v20, 0x37800000, v19
	v_cndmask_b32_e32 v19, v19, v20, vcc
	v_cmp_class_f32_e32 vcc, v18, v220
	s_nop 1
	v_cndmask_b32_e32 v18, v19, v18, vcc
	v_div_scale_f32 v19, s[4:5], v18, v18, 1.0
	v_rcp_f32_e32 v20, v19
	v_div_scale_f32 v21, vcc, 1.0, v18, 1.0
	v_fma_f32 v22, -v19, v20, 1.0
	v_fmac_f32_e32 v20, v22, v20
	v_mul_f32_e32 v22, v21, v20
	v_fma_f32 v23, -v19, v22, v21
	v_fmac_f32_e32 v22, v23, v20
	v_fma_f32 v19, -v19, v22, v21
	v_div_fmas_f32 v19, v19, v20, v22
	v_div_fixup_f32 v18, v19, v18, 1.0
	v_pk_mul_f32 v[20:21], v[26:27], v[18:19] op_sel_hi:[1,0]
	v_pk_mul_f32 v[22:23], v[28:29], v[18:19] op_sel_hi:[1,0]
	v_pk_mul_f32 v[24:25], v[30:31], v[18:19] op_sel_hi:[1,0]
	v_pk_mul_f32 v[26:27], v[32:33], v[18:19] op_sel_hi:[1,0]
	s_waitcnt vmcnt(2)
	v_pk_fma_f32 v[22:23], v[2:3], v[22:23], v[56:57]
	v_pk_fma_f32 v[2:3], v[4:5], v[20:21], v[54:55]
	v_pk_fma_f32 v[6:7], v[6:7], v[26:27], v[52:53]
	v_pk_fma_f32 v[4:5], v[8:9], v[24:25], v[50:51]
	v_cvt_pk_bf16_f32 v2, v2, v3
	v_cvt_pk_bf16_f32 v4, v4, v5
	v_cvt_pk_bf16_f32 v5, v6, v7
	v_lshl_add_u64 v[6:7], s[20:21], 0, v[184:185]
	v_add_co_u32_e32 v6, vcc, s46, v6
	v_cvt_pk_bf16_f32 v3, v22, v23
	s_nop 0
	v_addc_co_u32_e32 v7, vcc, 0, v7, vcc
	global_store_dwordx2 v[6:7], v[2:3], off
	global_store_dwordx2 v[6:7], v[4:5], off offset:512
	v_pk_mul_f32 v[8:9], v[58:59], v[18:19] op_sel_hi:[1,0]
	s_nop 0
	v_pk_mul_f32 v[4:5], v[36:37], v[18:19] op_sel_hi:[1,0]
	v_pk_mul_f32 v[2:3], v[34:35], v[18:19] op_sel_hi:[1,0]
	s_waitcnt vmcnt(1)
	v_pk_fma_f32 v[4:5], v[10:11], v[4:5], v[48:49]
	v_pk_mul_f32 v[10:11], v[60:61], v[18:19] op_sel_hi:[1,0]
	v_pk_fma_f32 v[2:3], v[12:13], v[2:3], v[46:47]
	v_pk_fma_f32 v[10:11], v[14:15], v[10:11], v[44:45]
	v_pk_fma_f32 v[8:9], v[16:17], v[8:9], v[42:43]
	v_cvt_pk_bf16_f32 v2, v2, v3
	v_cvt_pk_bf16_f32 v3, v4, v5
	v_cvt_pk_bf16_f32 v4, v8, v9
	v_cvt_pk_bf16_f32 v5, v10, v11
	global_store_dwordx2 v[6:7], v[2:3], off offset:1024
	global_store_dwordx2 v[6:7], v[4:5], off offset:1536

.LBB0_509:
	s_min_i32 s31, s34, 0x4000
	v_lshlrev_b32_e32 v147, 2, v128
	s_ashr_i32 s31, s31, 12
	global_load_dwordx4 v[34:37], v147, s[4:5] offset:1024 nt
	global_load_dwordx4 v[30:33], v147, s[4:5] nt
	global_load_dwordx4 v[80:83], v147, s[4:5] offset:3072 nt
	global_load_dwordx4 v[38:41], v147, s[4:5] offset:2048 nt
	s_mul_i32 s4, s31, 0x4800
	s_ashr_i32 s5, s4, 31
	s_lshl_b64 s[4:5], s[4:5], 2
	s_add_u32 s4, s16, s4
	s_addc_u32 s5, s17, s5
	global_load_dwordx4 v[6:9], v147, s[28:29] offset:1024 nt
	global_load_dwordx4 v[2:5], v147, s[28:29] nt
	global_load_dwordx4 v[58:61], v147, s[28:29] offset:3072 nt
	global_load_dwordx4 v[10:13], v147, s[28:29] offset:2048 nt
	s_add_u32 s28, s4, 0x1000
	s_addc_u32 s29, s5, 0
	global_load_dwordx4 v[50:53], v147, s[4:5] offset:1024
	global_load_dwordx4 v[54:57], v147, s[4:5]
	global_load_dwordx4 v[72:75], v147, s[28:29] offset:1024
	global_load_dwordx4 v[76:79], v147, s[28:29]
	global_load_dwordx4 v[42:45], v147, s[4:5] offset:3072
	global_load_dwordx4 v[46:49], v147, s[4:5] offset:2048
	global_load_dwordx4 v[62:65], v146, s[28:29] offset:1024
	global_load_dwordx4 v[68:71], v146, s[28:29]
	s_cmpk_gt_i32 s34, 0x3fff
	s_cselect_b64 s[4:5], -1, 0
	s_and_b64 s[28:29], s[6:7], s[4:5]
	s_mov_b64 s[4:5], -1
	s_and_b64 vcc, exec, s[28:29]
	s_cbranch_vccnz .LBB0_511
	s_waitcnt vmcnt(0)
	v_mov_b64_e32 v[14:15], v[30:31]
	s_mov_b64 s[4:5], 0
	v_mov_b32_e32 v87, v83
	v_mov_b32_e32 v86, v82
	v_mov_b32_e32 v85, v81
	v_mov_b32_e32 v84, v80
	v_mov_b64_e32 v[16:17], v[32:33]
	v_mov_b64_e32 v[18:19], v[34:35]
	v_mov_b64_e32 v[20:21], v[36:37]
	v_mov_b64_e32 v[22:23], v[38:39]
	v_mov_b64_e32 v[24:25], v[40:41]
	v_mov_b64_e32 v[26:27], v[42:43]
	v_mov_b64_e32 v[28:29], v[44:45]
.LBB0_511:
	v_cndmask_b32_e64 v26, 0, 1, s[0:1]
	s_andn2_b64 vcc, exec, s[4:5]
	v_cmp_ne_u32_e64 s[38:39], 1, v26
	s_cbranch_vccnz .LBB0_517
	v_lshl_add_u64 v[102:103], s[78:79], 2, v[130:131]
	v_add_co_u32_e32 v14, vcc, 0x400000, v102
	s_mov_b64 s[28:29], 0x400800
	s_nop 0
	v_addc_co_u32_e32 v15, vcc, 0, v103, vcc
	global_load_dwordx4 v[24:27], v[102:103], off
	global_load_dwordx4 v[88:91], v[14:15], off
	v_add_co_u32_e32 v14, vcc, 0x800000, v102
	v_lshl_add_u64 v[104:105], v[102:103], 0, s[28:29]
	s_nop 0
	v_addc_co_u32_e32 v15, vcc, 0, v103, vcc
	v_add_co_u32_e32 v16, vcc, 0xc00000, v102
	s_mov_b64 s[28:29], 0x800800
	s_nop 0
	v_addc_co_u32_e32 v17, vcc, 0, v103, vcc
	global_load_dwordx4 v[92:95], v[14:15], off
	global_load_dwordx4 v[96:99], v[16:17], off
	v_lshl_add_u64 v[106:107], v[102:103], 0, s[28:29]
	s_mov_b64 s[28:29], 0xc00800
	s_mov_b64 s[4:5], -1
	s_and_b64 vcc, exec, s[38:39]
	v_lshl_add_u64 v[100:101], v[102:103], 0, s[28:29]
	s_waitcnt vmcnt(0)
	v_pk_add_f32 v[108:109], v[30:31], v[24:25]
	s_cbranch_vccnz .LBB0_514
	v_add_co_u32_e32 v126, vcc, 0x1000000, v102
	v_lshl_add_u64 v[14:15], v[102:103], 0, s[66:67]
	s_nop 0
	v_addc_co_u32_e32 v127, vcc, 0, v103, vcc
	v_add_co_u32_e32 v172, vcc, 0x1400000, v102
	global_load_dwordx4 v[18:21], v[126:127], off
	s_nop 0
	global_load_dwordx4 v[14:17], v[14:15], off offset:1024
	v_addc_co_u32_e32 v173, vcc, 0, v103, vcc
	v_add_co_u32_e32 v28, vcc, s35, v102
	global_load_dwordx4 v[84:87], v[172:173], off
	global_load_dwordx4 v[22:25], v[102:103], off offset:1024
	v_addc_co_u32_e32 v29, vcc, 0, v103, vcc
	v_add_co_u32_e32 v176, vcc, 0x1800000, v102
	global_load_dwordx4 v[110:113], v[28:29], off offset:1024
	s_nop 0
	v_addc_co_u32_e32 v177, vcc, 0, v103, vcc
	v_add_co_u32_e32 v164, vcc, s72, v102
	global_load_dwordx4 v[114:117], v[176:177], off
	s_nop 0
	v_addc_co_u32_e32 v165, vcc, 0, v103, vcc
	v_add_co_u32_e32 v168, vcc, s73, v102
	global_load_dwordx4 v[118:121], v[164:165], off offset:1024
	s_nop 0
	v_addc_co_u32_e32 v169, vcc, 0, v103, vcc
	global_load_dwordx4 v[122:125], v[168:169], off offset:1024
	v_add_co_u32_e32 v166, vcc, 0x1c00000, v102
	v_lshl_add_u64 v[30:31], v[102:103], 0, s[80:81]
	s_nop 0
	v_addc_co_u32_e32 v167, vcc, 0, v103, vcc
	global_load_dwordx4 v[134:137], v[166:167], off
	global_load_dwordx4 v[138:141], v[30:31], off offset:1024
	v_lshl_add_u64 v[30:31], v[102:103], 0, s[74:75]
	global_load_dwordx4 v[148:151], v[30:31], off offset:1024
	v_lshl_add_u64 v[30:31], v[102:103], 0, s[84:85]
	global_load_dwordx4 v[152:155], v[30:31], off offset:1024
	global_load_dwordx4 v[156:159], v[102:103], off offset:2048
	global_load_dwordx4 v[160:163], v[28:29], off offset:2048
	v_pk_add_f32 v[28:29], v[32:33], v[26:27]
	v_pk_add_f32 v[30:31], v[88:89], v[108:109]
	v_pk_add_f32 v[170:171], v[90:91], v[28:29]
	v_pk_add_f32 v[174:175], v[92:93], v[30:31]
	v_pk_add_f32 v[170:171], v[94:95], v[170:171]
	global_load_dwordx4 v[28:31], v[102:103], off offset:3072
	v_pk_add_f32 v[174:175], v[96:97], v[174:175]
	s_mov_b64 s[4:5], 0x1000800
	s_waitcnt vmcnt(14)
	v_pk_add_f32 v[18:19], v[174:175], v[18:19]
	s_waitcnt vmcnt(12)
	v_pk_add_f32 v[18:19], v[84:85], v[18:19]
	s_waitcnt vmcnt(11)
	v_pk_add_f32 v[178:179], v[36:37], v[24:25]
	v_pk_add_f32 v[190:191], v[34:35], v[22:23]
	global_load_dwordx4 v[22:25], v[166:167], off offset:2048
	s_waitcnt vmcnt(11)
	v_pk_add_f32 v[178:179], v[112:113], v[178:179]
	v_pk_add_f32 v[190:191], v[110:111], v[190:191]
	global_load_dwordx4 v[110:113], v[164:165], off offset:2048
	s_waitcnt vmcnt(11)
	v_pk_add_f32 v[18:19], v[114:115], v[18:19]
	global_load_dwordx4 v[164:167], v[126:127], off offset:2048
	v_pk_add_f32 v[126:127], v[98:99], v[170:171]
	global_load_dwordx4 v[168:171], v[168:169], off offset:2048
	s_nop 0
	global_load_dwordx4 v[172:175], v[172:173], off offset:2048
	v_pk_add_f32 v[20:21], v[126:127], v[20:21]
	s_waitcnt vmcnt(13)
	v_pk_add_f32 v[126:127], v[120:121], v[178:179]
	v_pk_add_f32 v[178:179], v[118:119], v[190:191]
	v_pk_add_f32 v[20:21], v[86:87], v[20:21]
	s_waitcnt vmcnt(12)
	v_pk_add_f32 v[84:85], v[124:125], v[126:127]
	v_pk_add_f32 v[86:87], v[122:123], v[178:179]
	v_pk_add_f32 v[20:21], v[116:117], v[20:21]
	v_pk_add_f32 v[84:85], v[16:17], v[84:85]
	v_pk_add_f32 v[86:87], v[14:15], v[86:87]
	global_load_dwordx4 v[118:121], v[176:177], off offset:2048
	s_waitcnt vmcnt(12)
	v_pk_add_f32 v[16:17], v[136:137], v[20:21]
	v_pk_add_f32 v[14:15], v[134:135], v[18:19]
	s_waitcnt vmcnt(11)
	v_pk_add_f32 v[18:19], v[140:141], v[84:85]
	v_pk_add_f32 v[20:21], v[138:139], v[86:87]
	s_waitcnt vmcnt(10)
	v_pk_add_f32 v[18:19], v[150:151], v[18:19]
	v_pk_add_f32 v[84:85], v[148:149], v[20:21]
	s_waitcnt vmcnt(9)
	v_pk_add_f32 v[20:21], v[154:155], v[18:19]
	v_pk_add_f32 v[18:19], v[152:153], v[84:85]
	global_load_dwordx4 v[84:87], v[104:105], off offset:1024
	global_load_dwordx4 v[114:117], v[106:107], off offset:1024
	global_load_dwordx4 v[122:125], v[100:101], off offset:1024
	v_lshl_add_u64 v[126:127], v[102:103], 0, s[4:5]
	s_mov_b64 s[4:5], 0x1400800
	global_load_dwordx4 v[134:137], v[126:127], off offset:1024
	v_lshl_add_u64 v[126:127], v[102:103], 0, s[4:5]
	s_mov_b64 s[4:5], 0x1800800
	v_lshl_add_u64 v[148:149], v[102:103], 0, s[4:5]
	s_mov_b64 s[4:5], 0x1c00800
	global_load_dwordx4 v[138:141], v[126:127], off offset:1024
	s_nop 0
	global_load_dwordx4 v[148:151], v[148:149], off offset:1024
	s_waitcnt vmcnt(14)
	v_pk_add_f32 v[152:153], v[38:39], v[156:157]
	v_lshl_add_u64 v[154:155], v[102:103], 0, s[4:5]
	s_waitcnt vmcnt(13)
	v_pk_add_f32 v[156:157], v[160:161], v[152:153]
	global_load_dwordx4 v[152:155], v[154:155], off offset:1024
	v_pk_add_f32 v[126:127], v[40:41], v[158:159]
	s_waitcnt vmcnt(13)
	v_pk_add_f32 v[30:31], v[82:83], v[30:31]
	v_pk_add_f32 v[28:29], v[80:81], v[28:29]
	v_pk_add_f32 v[126:127], v[162:163], v[126:127]
	s_mov_b64 s[4:5], 0
	s_waitcnt vmcnt(11)
	v_pk_add_f32 v[112:113], v[112:113], v[126:127]
	v_pk_add_f32 v[110:111], v[110:111], v[156:157]
	s_waitcnt vmcnt(9)
	v_pk_add_f32 v[112:113], v[170:171], v[112:113]
	v_pk_add_f32 v[110:111], v[168:169], v[110:111]
	v_pk_add_f32 v[112:113], v[166:167], v[112:113]
	v_pk_add_f32 v[110:111], v[164:165], v[110:111]
	s_waitcnt vmcnt(8)
	v_pk_add_f32 v[112:113], v[174:175], v[112:113]
	v_pk_add_f32 v[110:111], v[172:173], v[110:111]
	s_waitcnt vmcnt(7)
	v_pk_add_f32 v[112:113], v[120:121], v[112:113]
	v_pk_add_f32 v[110:111], v[118:119], v[110:111]
	v_pk_add_f32 v[24:25], v[24:25], v[112:113]
	v_pk_add_f32 v[22:23], v[22:23], v[110:111]
	s_waitcnt vmcnt(6)
	v_pk_add_f32 v[30:31], v[86:87], v[30:31]
	v_pk_add_f32 v[28:29], v[84:85], v[28:29]
	s_waitcnt vmcnt(5)
	v_pk_add_f32 v[30:31], v[116:117], v[30:31]
	v_pk_add_f32 v[28:29], v[114:115], v[28:29]
	s_waitcnt vmcnt(4)
	v_pk_add_f32 v[30:31], v[124:125], v[30:31]
	v_pk_add_f32 v[28:29], v[122:123], v[28:29]
	s_waitcnt vmcnt(3)
	v_pk_add_f32 v[30:31], v[136:137], v[30:31]
	v_pk_add_f32 v[28:29], v[134:135], v[28:29]
	s_waitcnt vmcnt(2)
	v_pk_add_f32 v[30:31], v[140:141], v[30:31]
	v_pk_add_f32 v[28:29], v[138:139], v[28:29]
	s_waitcnt vmcnt(1)
	v_pk_add_f32 v[30:31], v[150:151], v[30:31]
	v_pk_add_f32 v[28:29], v[148:149], v[28:29]
	s_waitcnt vmcnt(0)
	v_pk_add_f32 v[86:87], v[154:155], v[30:31]
	v_pk_add_f32 v[84:85], v[152:153], v[28:29]
.LBB0_514:
	s_andn2_b64 vcc, exec, s[4:5]
	s_cbranch_vccnz .LBB0_516
	v_pk_add_f32 v[14:15], v[32:33], v[26:27]
	v_add_co_u32_e32 v84, vcc, s35, v102
	v_pk_add_f32 v[14:15], v[90:91], v[14:15]
	v_pk_add_f32 v[16:17], v[88:89], v[108:109]
	v_addc_co_u32_e32 v85, vcc, 0, v103, vcc
	v_pk_add_f32 v[14:15], v[94:95], v[14:15]
	v_pk_add_f32 v[18:19], v[92:93], v[16:17]
	v_add_co_u32_e32 v86, vcc, s72, v102
	v_pk_add_f32 v[16:17], v[98:99], v[14:15]
	v_pk_add_f32 v[14:15], v[96:97], v[18:19]
	global_load_dwordx4 v[18:21], v[102:103], off offset:1024
	v_addc_co_u32_e32 v87, vcc, 0, v103, vcc
	global_load_dwordx4 v[22:25], v[84:85], off offset:1024
	global_load_dwordx4 v[26:29], v[86:87], off offset:1024
	v_add_co_u32_e32 v92, vcc, s73, v102
	s_nop 1
	v_addc_co_u32_e32 v93, vcc, 0, v103, vcc
	global_load_dwordx4 v[30:33], v[92:93], off offset:1024
	s_waitcnt vmcnt(3)
	v_pk_add_f32 v[20:21], v[36:37], v[20:21]
	v_pk_add_f32 v[18:19], v[34:35], v[18:19]
	s_waitcnt vmcnt(2)
	v_pk_add_f32 v[20:21], v[24:25], v[20:21]
	v_pk_add_f32 v[18:19], v[22:23], v[18:19]
	s_waitcnt vmcnt(1)
	v_pk_add_f32 v[20:21], v[28:29], v[20:21]
	v_pk_add_f32 v[18:19], v[26:27], v[18:19]
	s_waitcnt vmcnt(0)
	v_pk_add_f32 v[20:21], v[32:33], v[20:21]
	v_pk_add_f32 v[18:19], v[30:31], v[18:19]
	global_load_dwordx4 v[26:29], v[102:103], off offset:3072
	global_load_dwordx4 v[22:25], v[102:103], off offset:2048
	global_load_dwordx4 v[30:33], v[84:85], off offset:2048
	global_load_dwordx4 v[34:37], v[104:105], off offset:1024
	s_nop 0
	global_load_dwordx4 v[84:87], v[86:87], off offset:2048
	s_nop 0
	global_load_dwordx4 v[88:91], v[106:107], off offset:1024
	s_nop 0
	global_load_dwordx4 v[92:95], v[92:93], off offset:2048
	s_nop 0
	global_load_dwordx4 v[96:99], v[100:101], off offset:1024
	s_waitcnt vmcnt(7)
	v_pk_add_f32 v[28:29], v[82:83], v[28:29]
	s_waitcnt vmcnt(6)
	v_pk_add_f32 v[24:25], v[40:41], v[24:25]
	v_pk_add_f32 v[22:23], v[38:39], v[22:23]
	v_pk_add_f32 v[26:27], v[80:81], v[26:27]
	s_waitcnt vmcnt(5)
	v_pk_add_f32 v[24:25], v[32:33], v[24:25]
	v_pk_add_f32 v[22:23], v[30:31], v[22:23]
	s_waitcnt vmcnt(4)
	v_pk_add_f32 v[28:29], v[36:37], v[28:29]
	v_pk_add_f32 v[26:27], v[34:35], v[26:27]
	s_waitcnt vmcnt(3)
	v_pk_add_f32 v[24:25], v[86:87], v[24:25]
	v_pk_add_f32 v[22:23], v[84:85], v[22:23]
	s_waitcnt vmcnt(2)
	v_pk_add_f32 v[28:29], v[90:91], v[28:29]
	v_pk_add_f32 v[26:27], v[88:89], v[26:27]
	s_waitcnt vmcnt(1)
	v_pk_add_f32 v[24:25], v[94:95], v[24:25]
	v_pk_add_f32 v[22:23], v[92:93], v[22:23]
	s_waitcnt vmcnt(0)
	v_pk_add_f32 v[86:87], v[98:99], v[28:29]
	v_pk_add_f32 v[84:85], v[96:97], v[26:27]
.LBB0_516:
	s_nop 0
	v_mov_b64_e32 v[80:81], v[84:85]
	v_lshl_add_u64 v[26:27], s[78:79], 2, v[132:133]
	v_mov_b64_e32 v[82:83], v[86:87]
	global_store_dwordx4 v[26:27], v[14:17], off
	global_store_dwordx4 v[26:27], v[18:21], off offset:1024
	global_store_dwordx4 v[26:27], v[22:25], off offset:2048
	global_store_dwordx4 v[26:27], v[84:87], off offset:3072

.LBB0_519:
	s_andn2_b64 vcc, exec, s[4:5]
	s_cbranch_vccnz .LBB0_525
	s_add_i32 s4, s55, s78
	s_mov_b32 s5, s79
	v_lshl_add_u64 v[134:135], s[4:5], 2, v[130:131]
	v_add_co_u32_e32 v26, vcc, 0x400000, v134
	s_mov_b64 s[28:29], -1
	s_nop 0
	v_addc_co_u32_e32 v27, vcc, 0, v135, vcc
	global_load_dwordx4 v[36:39], v[134:135], off
	global_load_dwordx4 v[88:91], v[26:27], off
	v_add_co_u32_e32 v26, vcc, 0x800000, v134
	s_waitcnt vmcnt(0)
	v_pk_add_f32 v[2:3], v[2:3], v[36:37]
	v_addc_co_u32_e32 v27, vcc, 0, v135, vcc
	v_add_co_u32_e32 v28, vcc, 0xc00000, v134
	s_nop 1
	v_addc_co_u32_e32 v29, vcc, 0, v135, vcc
	global_load_dwordx4 v[92:95], v[26:27], off
	global_load_dwordx4 v[96:99], v[28:29], off
	s_and_b64 vcc, exec, s[38:39]
	s_mov_b64 s[38:39], 0x400800
	v_lshl_add_u64 v[136:137], v[134:135], 0, s[38:39]
	s_mov_b64 s[38:39], 0x800800
	v_lshl_add_u64 v[138:139], v[134:135], 0, s[38:39]
	s_mov_b64 s[38:39], 0xc00800
	v_lshl_add_u64 v[40:41], v[134:135], 0, s[38:39]
	s_cbranch_vccnz .LBB0_522
	v_add_co_u32_e32 v34, vcc, 0x1000000, v134
	v_lshl_add_u64 v[30:31], v[134:135], 0, s[66:67]
	s_nop 0
	v_addc_co_u32_e32 v35, vcc, 0, v135, vcc
	v_add_co_u32_e32 v36, vcc, 0x1400000, v134
	global_load_dwordx4 v[26:29], v[34:35], off
	s_nop 0
	global_load_dwordx4 v[30:33], v[30:31], off offset:1024
	v_addc_co_u32_e32 v37, vcc, 0, v135, vcc
	v_add_co_u32_e32 v124, vcc, 0x1800000, v134
	v_lshl_add_u64 v[104:105], v[134:135], 0, s[80:81]
	s_nop 0
	v_addc_co_u32_e32 v125, vcc, 0, v135, vcc
	global_load_dwordx4 v[100:103], v[36:37], off
	s_nop 0
	global_load_dwordx4 v[104:107], v[104:105], off offset:1024
	v_lshl_add_u64 v[112:113], v[134:135], 0, s[74:75]
	v_add_co_u32_e32 v140, vcc, 0x1c00000, v134
	global_load_dwordx4 v[108:111], v[124:125], off
	s_nop 0
	global_load_dwordx4 v[112:115], v[112:113], off offset:1024
	v_lshl_add_u64 v[120:121], v[134:135], 0, s[84:85]
	v_addc_co_u32_e32 v141, vcc, 0, v135, vcc
	global_load_dwordx4 v[116:119], v[140:141], off
	s_nop 0
	global_load_dwordx4 v[120:123], v[120:121], off offset:1024
	v_pk_add_f32 v[126:127], v[4:5], v[38:39]
	v_pk_add_f32 v[148:149], v[88:89], v[2:3]
	v_pk_add_f32 v[126:127], v[90:91], v[126:127]
	s_waitcnt vmcnt(9)
	v_pk_add_f32 v[148:149], v[92:93], v[148:149]
	v_pk_add_f32 v[126:127], v[94:95], v[126:127]
	s_waitcnt vmcnt(8)
	v_pk_add_f32 v[148:149], v[96:97], v[148:149]
	v_pk_add_f32 v[126:127], v[98:99], v[126:127]
	s_mov_b64 s[28:29], 0x1000800
	s_waitcnt vmcnt(7)
	v_pk_add_f32 v[28:29], v[126:127], v[28:29]
	v_add_co_u32_e32 v126, vcc, s35, v134
	v_pk_add_f32 v[26:27], v[148:149], v[26:27]
	s_nop 0
	v_addc_co_u32_e32 v127, vcc, 0, v135, vcc
	v_add_co_u32_e32 v156, vcc, s72, v134
	s_waitcnt vmcnt(5)
	v_pk_add_f32 v[28:29], v[102:103], v[28:29]
	v_pk_add_f32 v[26:27], v[100:101], v[26:27]
	global_load_dwordx4 v[100:103], v[134:135], off offset:1024
	v_addc_co_u32_e32 v157, vcc, 0, v135, vcc
	s_waitcnt vmcnt(4)
	v_pk_add_f32 v[28:29], v[110:111], v[28:29]
	v_pk_add_f32 v[26:27], v[108:109], v[26:27]
	global_load_dwordx4 v[108:111], v[126:127], off offset:1024
	v_add_co_u32_e32 v160, vcc, s73, v134
	s_waitcnt vmcnt(3)
	v_pk_add_f32 v[28:29], v[118:119], v[28:29]
	v_pk_add_f32 v[26:27], v[116:117], v[26:27]
	global_load_dwordx4 v[116:119], v[156:157], off offset:1024
	v_addc_co_u32_e32 v161, vcc, 0, v135, vcc
	global_load_dwordx4 v[148:151], v[160:161], off offset:1024
	s_waitcnt vmcnt(3)
	v_pk_add_f32 v[102:103], v[8:9], v[102:103]
	v_pk_add_f32 v[100:101], v[6:7], v[100:101]
	s_waitcnt vmcnt(2)
	v_pk_add_f32 v[102:103], v[110:111], v[102:103]
	v_pk_add_f32 v[100:101], v[108:109], v[100:101]
	s_waitcnt vmcnt(1)
	v_pk_add_f32 v[102:103], v[118:119], v[102:103]
	v_pk_add_f32 v[100:101], v[116:117], v[100:101]
	v_lshl_add_u64 v[116:117], v[134:135], 0, s[28:29]
	s_waitcnt vmcnt(0)
	v_pk_add_f32 v[102:103], v[150:151], v[102:103]
	v_pk_add_f32 v[100:101], v[148:149], v[100:101]
	v_pk_add_f32 v[32:33], v[32:33], v[102:103]
	v_pk_add_f32 v[30:31], v[30:31], v[100:101]
	v_pk_add_f32 v[32:33], v[106:107], v[32:33]
	v_pk_add_f32 v[30:31], v[104:105], v[30:31]
	v_pk_add_f32 v[32:33], v[114:115], v[32:33]
	v_pk_add_f32 v[30:31], v[112:113], v[30:31]
	global_load_dwordx4 v[100:103], v[134:135], off offset:3072
	global_load_dwordx4 v[148:151], v[134:135], off offset:2048
	global_load_dwordx4 v[152:155], v[126:127], off offset:2048
	global_load_dwordx4 v[104:107], v[136:137], off offset:1024
	s_nop 0
	global_load_dwordx4 v[156:159], v[156:157], off offset:2048
	s_nop 0
	global_load_dwordx4 v[108:111], v[138:139], off offset:1024
	s_nop 0
	global_load_dwordx4 v[160:163], v[160:161], off offset:2048
	s_nop 0
	global_load_dwordx4 v[112:115], v[40:41], off offset:1024
	s_mov_b64 s[28:29], 0x1400800
	v_pk_add_f32 v[30:31], v[120:121], v[30:31]
	global_load_dwordx4 v[164:167], v[34:35], off offset:2048
	s_nop 0
	global_load_dwordx4 v[116:119], v[116:117], off offset:1024
	v_lshl_add_u64 v[120:121], v[134:135], 0, s[28:29]
	s_mov_b64 s[28:29], 0x1800800
	v_pk_add_f32 v[32:33], v[122:123], v[32:33]
	global_load_dwordx4 v[34:37], v[36:37], off offset:2048
	s_nop 0
	global_load_dwordx4 v[120:123], v[120:121], off offset:1024
	v_lshl_add_u64 v[126:127], v[134:135], 0, s[28:29]
	s_mov_b64 s[28:29], 0x1c00800
	global_load_dwordx4 v[168:171], v[124:125], off offset:2048
	s_nop 0
	global_load_dwordx4 v[124:127], v[126:127], off offset:1024
	v_lshl_add_u64 v[176:177], v[134:135], 0, s[28:29]
	global_load_dwordx4 v[172:175], v[140:141], off offset:2048
	s_nop 0
	global_load_dwordx4 v[176:179], v[176:177], off offset:1024
	s_mov_b64 s[28:29], 0
	s_waitcnt vmcnt(15)
	v_pk_add_f32 v[102:103], v[60:61], v[102:103]
	s_waitcnt vmcnt(14)
	v_pk_add_f32 v[140:141], v[12:13], v[150:151]
	v_pk_add_f32 v[148:149], v[10:11], v[148:149]
	v_pk_add_f32 v[100:101], v[58:59], v[100:101]
	s_waitcnt vmcnt(13)
	v_pk_add_f32 v[140:141], v[154:155], v[140:141]
	v_pk_add_f32 v[148:149], v[152:153], v[148:149]
	s_waitcnt vmcnt(12)
	v_pk_add_f32 v[102:103], v[106:107], v[102:103]
	v_pk_add_f32 v[100:101], v[104:105], v[100:101]
	s_waitcnt vmcnt(11)
	v_pk_add_f32 v[140:141], v[158:159], v[140:141]
	v_pk_add_f32 v[148:149], v[156:157], v[148:149]
	s_waitcnt vmcnt(10)
	v_pk_add_f32 v[102:103], v[110:111], v[102:103]
	v_pk_add_f32 v[100:101], v[108:109], v[100:101]
	s_waitcnt vmcnt(9)
	v_pk_add_f32 v[140:141], v[162:163], v[140:141]
	v_pk_add_f32 v[148:149], v[160:161], v[148:149]
	s_waitcnt vmcnt(8)
	v_pk_add_f32 v[102:103], v[114:115], v[102:103]
	v_pk_add_f32 v[100:101], v[112:113], v[100:101]
	s_waitcnt vmcnt(7)
	v_pk_add_f32 v[140:141], v[166:167], v[140:141]
	v_pk_add_f32 v[148:149], v[164:165], v[148:149]
	s_waitcnt vmcnt(6)
	v_pk_add_f32 v[102:103], v[118:119], v[102:103]
	v_pk_add_f32 v[100:101], v[116:117], v[100:101]
	s_waitcnt vmcnt(5)
	v_pk_add_f32 v[36:37], v[36:37], v[140:141]
	v_pk_add_f32 v[34:35], v[34:35], v[148:149]
	s_waitcnt vmcnt(4)
	v_pk_add_f32 v[102:103], v[122:123], v[102:103]
	v_pk_add_f32 v[100:101], v[120:121], v[100:101]
	s_waitcnt vmcnt(3)
	v_pk_add_f32 v[36:37], v[170:171], v[36:37]
	v_pk_add_f32 v[34:35], v[168:169], v[34:35]
	s_waitcnt vmcnt(2)
	v_pk_add_f32 v[102:103], v[126:127], v[102:103]
	v_pk_add_f32 v[100:101], v[124:125], v[100:101]
	s_waitcnt vmcnt(1)
	v_pk_add_f32 v[36:37], v[174:175], v[36:37]
	v_pk_add_f32 v[34:35], v[172:173], v[34:35]
	s_waitcnt vmcnt(0)
	v_pk_add_f32 v[102:103], v[178:179], v[102:103]
	v_pk_add_f32 v[100:101], v[176:177], v[100:101]
.LBB0_522:
	s_andn2_b64 vcc, exec, s[28:29]
	s_cbranch_vccnz .LBB0_524
	v_pk_add_f32 v[4:5], v[4:5], v[38:39]
	v_add_co_u32_e32 v38, vcc, s35, v134
	v_pk_add_f32 v[4:5], v[90:91], v[4:5]
	v_pk_add_f32 v[2:3], v[88:89], v[2:3]
	v_addc_co_u32_e32 v39, vcc, 0, v135, vcc
	s_waitcnt vmcnt(1)
	v_pk_add_f32 v[4:5], v[94:95], v[4:5]
	v_pk_add_f32 v[2:3], v[92:93], v[2:3]
	v_add_co_u32_e32 v92, vcc, s72, v134
	s_waitcnt vmcnt(0)
	v_pk_add_f32 v[28:29], v[98:99], v[4:5]
	v_pk_add_f32 v[26:27], v[96:97], v[2:3]
	global_load_dwordx4 v[2:5], v[134:135], off offset:1024
	v_addc_co_u32_e32 v93, vcc, 0, v135, vcc
	global_load_dwordx4 v[30:33], v[38:39], off offset:1024
	global_load_dwordx4 v[34:37], v[92:93], off offset:1024
	v_add_co_u32_e32 v100, vcc, s73, v134
	s_nop 1
	v_addc_co_u32_e32 v101, vcc, 0, v135, vcc
	global_load_dwordx4 v[88:91], v[100:101], off offset:1024
	s_waitcnt vmcnt(3)
	v_pk_add_f32 v[4:5], v[8:9], v[4:5]
	v_pk_add_f32 v[2:3], v[6:7], v[2:3]
	s_waitcnt vmcnt(2)
	v_pk_add_f32 v[4:5], v[32:33], v[4:5]
	v_pk_add_f32 v[2:3], v[30:31], v[2:3]
	s_waitcnt vmcnt(1)
	v_pk_add_f32 v[4:5], v[36:37], v[4:5]
	v_pk_add_f32 v[2:3], v[34:35], v[2:3]
	s_waitcnt vmcnt(0)
	v_pk_add_f32 v[32:33], v[90:91], v[4:5]
	v_pk_add_f32 v[30:31], v[88:89], v[2:3]
	global_load_dwordx4 v[2:5], v[134:135], off offset:3072
	global_load_dwordx4 v[6:9], v[134:135], off offset:2048
	global_load_dwordx4 v[34:37], v[38:39], off offset:2048
	global_load_dwordx4 v[88:91], v[136:137], off offset:1024
	s_nop 0
	global_load_dwordx4 v[92:95], v[92:93], off offset:2048
	s_nop 0
	global_load_dwordx4 v[96:99], v[138:139], off offset:1024
	s_nop 0
	global_load_dwordx4 v[100:103], v[100:101], off offset:2048
	s_nop 0
	global_load_dwordx4 v[38:41], v[40:41], off offset:1024
	s_waitcnt vmcnt(7)
	v_pk_add_f32 v[4:5], v[60:61], v[4:5]
	s_waitcnt vmcnt(6)
	v_pk_add_f32 v[8:9], v[12:13], v[8:9]
	v_pk_add_f32 v[6:7], v[10:11], v[6:7]
	v_pk_add_f32 v[2:3], v[58:59], v[2:3]
	s_waitcnt vmcnt(5)
	v_pk_add_f32 v[8:9], v[36:37], v[8:9]
	v_pk_add_f32 v[6:7], v[34:35], v[6:7]
	s_waitcnt vmcnt(4)
	v_pk_add_f32 v[4:5], v[90:91], v[4:5]
	v_pk_add_f32 v[2:3], v[88:89], v[2:3]
	s_waitcnt vmcnt(3)
	v_pk_add_f32 v[8:9], v[94:95], v[8:9]
	v_pk_add_f32 v[6:7], v[92:93], v[6:7]
	s_waitcnt vmcnt(2)
	v_pk_add_f32 v[4:5], v[98:99], v[4:5]
	v_pk_add_f32 v[2:3], v[96:97], v[2:3]
	s_waitcnt vmcnt(1)
	v_pk_add_f32 v[36:37], v[102:103], v[8:9]
	v_pk_add_f32 v[34:35], v[100:101], v[6:7]
	s_waitcnt vmcnt(0)
	v_pk_add_f32 v[102:103], v[40:41], v[4:5]
	v_pk_add_f32 v[100:101], v[38:39], v[2:3]
.LBB0_524:
	s_nop 0
	v_mov_b64_e32 v[58:59], v[100:101]
	v_lshl_add_u64 v[2:3], s[4:5], 2, v[132:133]
	v_mov_b64_e32 v[60:61], v[102:103]
	global_store_dwordx4 v[2:3], v[26:29], off
	global_store_dwordx4 v[2:3], v[30:33], off offset:1024
	global_store_dwordx4 v[2:3], v[34:37], off offset:2048
	global_store_dwordx4 v[2:3], v[100:103], off offset:3072
.LBB0_525:
	s_waitcnt vmcnt(0)
	v_pk_mul_f32 v[6:7], v[16:17], v[16:17]
	v_pk_mul_f32 v[8:9], v[14:15], v[14:15]
	v_pk_mul_f32 v[2:3], v[20:21], v[20:21]
	v_pk_mul_f32 v[4:5], v[18:19], v[18:19]
	v_pk_mov_b32 v[10:11], v[8:9], v[6:7] op_sel:[1,0]
	v_mov_b32_e32 v9, v7
	v_pk_add_f32 v[6:7], v[10:11], v[8:9]
	v_pk_mov_b32 v[8:9], v[4:5], v[2:3] op_sel:[1,0]
	v_mov_b32_e32 v5, v3
	v_pk_add_f32 v[2:3], v[8:9], v[4:5]
	v_pk_add_f32 v[6:7], v[6:7], v[6:7] op_sel_hi:[0,1]
	v_pk_add_f32 v[2:3], v[2:3], v[2:3] op_sel_hi:[0,1]
	v_mul_f32_e32 v2, v22, v22
	v_pk_fma_f32 v[4:5], v[22:23], v[22:23], v[2:3] op_sel_hi:[1,1,0]
	v_mul_f32_e32 v2, v24, v24
	v_pk_fma_f32 v[8:9], v[24:25], v[24:25], v[2:3] op_sel_hi:[1,1,0]
	v_mul_f32_e32 v4, v84, v84
	v_mul_f32_e32 v8, v85, v85
	v_mul_f32_e32 v6, v86, v86
	v_mul_f32_e32 v2, v87, v87
	v_pk_add_f32 v[4:5], v[4:5], v[8:9]
	v_pk_add_f32 v[2:3], v[6:7], v[2:3]
	s_nop 0
	v_pk_add_f32 v[2:3], v[4:5], v[2:3]
	s_nop 0
	v_add_f32_e32 v2, v2, v3
	s_nop 1
	v_add_f32_dpp v2, v2, v2 quad_perm:[1,0,3,2] row_mask:0xf bank_mask:0xf
	s_nop 1
	v_add_f32_dpp v2, v2, v2 quad_perm:[2,3,0,1] row_mask:0xf bank_mask:0xf
	s_nop 1
	v_add_f32_dpp v2, v2, v2 row_half_mirror row_mask:0xf bank_mask:0xf
	s_nop 1
	v_add_f32_dpp v2, v2, v2 row_mirror row_mask:0xf bank_mask:0xf
	s_nop 1
	v_mov_b32_e32 v3, v2
	s_nop 1
	v_permlane16_swap_b32_e32 v2, v3
	s_nop 1
	v_add_f32_e32 v2, v2, v3
	s_nop 1
	v_mov_b32_e32 v3, v2
	s_nop 1
	v_permlane32_swap_b32_e32 v2, v3
	s_nop 1
	v_add_f32_e32 v2, v2, v3
	v_fmamk_f32 v2, v2, 0x3a800000, v1
	v_mul_f32_e32 v3, 0x4f800000, v2
	v_cmp_gt_f32_e32 vcc, s56, v2
	s_nop 1
	v_cndmask_b32_e32 v4, v2, v3, vcc
	v_sqrt_f32_e32 v5, v4
	v_pk_add_f32 v[2:3], v[78:79], 1.0 op_sel_hi:[1,0]
	v_add_u32_e32 v6, -1, v5
	v_add_u32_e32 v7, 1, v5
	v_fma_f32 v8, -v6, v5, v4
	v_fma_f32 v9, -v7, v5, v4
	v_cmp_ge_f32_e64 s[38:39], 0, v8
	s_nop 1
	v_cndmask_b32_e64 v5, v5, v6, s[38:39]
	v_cmp_lt_f32_e64 s[38:39], 0, v9
	s_nop 1
	v_cndmask_b32_e64 v5, v5, v7, s[38:39]
	v_mul_f32_e32 v6, 0x37800000, v5
	v_cndmask_b32_e32 v5, v5, v6, vcc
	v_cmp_class_f32_e32 vcc, v4, v220
	s_nop 1
	v_cndmask_b32_e32 v6, v5, v4, vcc
	v_div_scale_f32 v7, s[4:5], v6, v6, 1.0
	v_rcp_f32_e32 v8, v7
	v_div_scale_f32 v9, vcc, 1.0, v6, 1.0
	v_pk_add_f32 v[4:5], v[76:77], 1.0 op_sel_hi:[1,0]
	v_fma_f32 v10, -v7, v8, 1.0
	v_fmac_f32_e32 v8, v10, v8
	v_mul_f32_e32 v10, v9, v8
	v_fma_f32 v11, -v7, v10, v9
	v_fmac_f32_e32 v10, v11, v8
	v_fma_f32 v7, -v7, v10, v9
	v_div_fmas_f32 v7, v7, v8, v10
	v_div_fixup_f32 v38, v7, v6, 1.0
	v_pk_mul_f32 v[8:9], v[16:17], v[38:39] op_sel_hi:[1,0]
	v_pk_mul_f32 v[6:7], v[14:15], v[38:39] op_sel_hi:[1,0]
	v_pk_fma_f32 v[12:13], v[2:3], v[8:9], v[56:57]
	v_pk_mul_f32 v[14:15], v[18:19], v[38:39] op_sel_hi:[1,0]
	v_pk_add_f32 v[8:9], v[72:73], 1.0 op_sel_hi:[1,0]
	v_pk_fma_f32 v[10:11], v[4:5], v[6:7], v[54:55]
	v_pk_fma_f32 v[14:15], v[8:9], v[14:15], v[50:51]
	v_pk_mul_f32 v[16:17], v[20:21], v[38:39] op_sel_hi:[1,0]
	v_pk_add_f32 v[6:7], v[74:75], 1.0 op_sel_hi:[1,0]
	v_cvt_pk_bf16_f32 v10, v10, v11
	v_cvt_pk_bf16_f32 v11, v12, v13
	v_cvt_pk_bf16_f32 v12, v14, v15
	v_lshl_add_u64 v[14:15], s[10:11], 0, v[184:185]
	v_pk_fma_f32 v[16:17], v[6:7], v[16:17], v[52:53]
	v_add_co_u32_e32 v40, vcc, s46, v14
	v_cvt_pk_bf16_f32 v13, v16, v17
	s_nop 0
	v_addc_co_u32_e32 v41, vcc, 0, v15, vcc
	global_store_dwordx2 v[40:41], v[10:11], off
	global_store_dwordx2 v[40:41], v[12:13], off offset:512
	v_pk_mul_f32 v[14:15], v[22:23], v[38:39] op_sel_hi:[1,0]
	v_pk_mul_f32 v[16:17], v[24:25], v[38:39] op_sel_hi:[1,0]
	v_pk_add_f32 v[10:11], v[70:71], 1.0 op_sel_hi:[1,0]
	v_pk_add_f32 v[12:13], v[68:69], 1.0 op_sel_hi:[1,0]
	v_pk_fma_f32 v[20:21], v[10:11], v[16:17], v[48:49]
	v_pk_fma_f32 v[18:19], v[12:13], v[14:15], v[46:47]
	v_pk_mul_f32 v[22:23], v[80:81], v[38:39] op_sel_hi:[1,0]
	v_pk_mul_f32 v[24:25], v[82:83], v[38:39] op_sel_hi:[1,0]
	v_pk_add_f32 v[14:15], v[64:65], 1.0 op_sel_hi:[1,0]
	v_pk_add_f32 v[16:17], v[62:63], 1.0 op_sel_hi:[1,0]
	v_pk_fma_f32 v[24:25], v[14:15], v[24:25], v[44:45]
	v_pk_fma_f32 v[22:23], v[16:17], v[22:23], v[42:43]
	v_cvt_pk_bf16_f32 v18, v18, v19
	v_cvt_pk_bf16_f32 v19, v20, v21
	v_cvt_pk_bf16_f32 v20, v22, v23
	v_cvt_pk_bf16_f32 v21, v24, v25
	s_andn2_b64 vcc, exec, s[40:41]
	global_store_dwordx2 v[40:41], v[18:19], off offset:1024
	global_store_dwordx2 v[40:41], v[20:21], off offset:1536
	s_cbranch_vccnz .LBB0_505
	s_min_i32 s4, s30, 0x4000
	s_ashr_i32 s4, s4, 12
	s_cmp_eq_u32 s4, s31
	s_cbranch_scc1 .LBB0_504
	s_mulk_i32 s4, 0x4800
	s_ashr_i32 s5, s4, 31
	s_lshl_b64 s[4:5], s[4:5], 2
	s_add_u32 s4, s16, s4
	s_addc_u32 s5, s17, s5
	s_add_u32 s28, s4, 0x1000
	s_addc_u32 s29, s5, 0
	global_load_dwordx4 v[4:7], v147, s[28:29]
	global_load_dwordx4 v[8:11], v147, s[28:29] offset:1024
	global_load_dwordx4 v[16:19], v146, s[28:29] offset:1024
	global_load_dwordx4 v[12:15], v146, s[28:29]
	global_load_dwordx4 v[50:53], v147, s[4:5] offset:1024
	global_load_dwordx4 v[54:57], v147, s[4:5]
	global_load_dwordx4 v[42:45], v147, s[4:5] offset:3072
	global_load_dwordx4 v[46:49], v147, s[4:5] offset:2048
	s_waitcnt vmcnt(7)
	v_pk_add_f32 v[2:3], v[6:7], 1.0 op_sel_hi:[1,0]
	v_pk_add_f32 v[4:5], v[4:5], 1.0 op_sel_hi:[1,0]
	s_waitcnt vmcnt(6)
	v_pk_add_f32 v[6:7], v[10:11], 1.0 op_sel_hi:[1,0]
	v_pk_add_f32 v[8:9], v[8:9], 1.0 op_sel_hi:[1,0]
	s_waitcnt vmcnt(4)
	v_pk_add_f32 v[10:11], v[14:15], 1.0 op_sel_hi:[1,0]
	v_pk_add_f32 v[12:13], v[12:13], 1.0 op_sel_hi:[1,0]
	v_pk_add_f32 v[14:15], v[18:19], 1.0 op_sel_hi:[1,0]
	v_pk_add_f32 v[16:17], v[16:17], 1.0 op_sel_hi:[1,0]
	s_branch .LBB0_504
